# v79 + in-proj tile headers: the generic u32 division by the group size (always 4) replaced by a shift
# baseline (speedup 1.0000x reference)
;     __host__ __device__ bool next(int i, Unit& u) const {
;         const long L = (long)i * G + c; if (L >= nwg) return false;
;         int wgid = (int)L; { const int q = nwg / NXCD, r = nwg % NXCD, xcd = wgid % NXCD, off = wgid / NXCD; wgid = (xcd < r ? xcd * (q + 1) : r * (q + 1) + (xcd - r) * q) + off; }
;         const int nig = WGM * nN, gid = wgid / nig, fm = gid * WGM, gsz = (nM - fm) < WGM ? (nM - fm) : WGM;
;         u.pm = fm + ((wgid % nig) % gsz); u.pn = (wgid % nig) / gsz; return true;
.LBB0_124:
	s_ashr_i32 s5, s5, 3
	s_add_i32 s5, s31, s5
	s_ashr_i32 s28, s5, 31
	s_lshr_b32 s28, s28, 26
	s_add_i32 s28, s5, s28
	s_ashr_i32 s29, s28, 6
	s_lshl_b32 s29, s29, 2
	s_sub_i32 s30, 0x80, s29
	s_min_i32 s30, s30, 4
	s_andn2_b32 s28, s28, 63
	s_sub_i32 s5, s5, s28
	s_ashr_i32 s28, s5, 2
	s_mul_i32 s30, s28, s30
	s_sub_i32 s5, s5, s30
	s_add_i32 s30, s29, s5

;     __device__ bool next(int i, Unit& u) const { return i == 0 && base.next(round, u); }
;     __host__ __device__ bool next(int i, Unit& u) const {
;         const long L = (long)i * G + c; if (L >= nwg) return false;
;         int wgid = (int)L; { const int q = nwg / NXCD, r = nwg % NXCD, xcd = wgid % NXCD, off = wgid / NXCD; wgid = (xcd < r ? xcd * (q + 1) : r * (q + 1) + (xcd - r) * q) + off; }
;         const int nig = WGM * nN, gid = wgid / nig, fm = gid * WGM, gsz = (nM - fm) < WGM ? (nM - fm) : WGM;
;         u.pm = fm + ((wgid % nig) % gsz); u.pn = (wgid % nig) / gsz; return true;
.LBB0_171:
	s_add_i32 s53, s53, 1
	s_mul_i32 s0, s53, s60
	s_mul_hi_u32 s1, s53, s61
	s_add_i32 s1, s1, s0
	s_mul_i32 s0, s53, s61
	s_add_u32 s4, s0, s2
	s_addc_u32 s5, s1, s47
	v_cmp_gt_i64_e32 vcc, s[4:5], v[152:153]
	v_cmp_lt_i64_e64 s[0:1], s[4:5], v[150:151]
	s_cbranch_vccnz .LBB0_173
	s_ashr_i32 s5, s4, 31
	s_lshr_b32 s5, s5, 29
	s_add_i32 s5, s4, s5
	s_ashr_i32 s28, s5, 3
	s_and_b32 s5, s5, -8
	s_sub_i32 s4, s4, s5
	s_cmp_lt_i32 s4, 0
	s_cselect_b32 s5, s48, 0x120
	s_mul_i32 s4, s4, s5
	s_add_i32 s4, s4, s28
	s_mul_hi_i32 s5, s4, 0x38e38e39
	s_lshr_b32 s28, s5, 31
	s_ashr_i32 s5, s5, 4
	s_add_i32 s5, s5, s28
	s_lshl_b32 s28, s5, 2
	s_sub_i32 s29, 0x80, s28
	s_min_i32 s29, s29, 4
	s_mulk_i32 s5, 0x48
	s_sub_i32 s4, s4, s5
	s_ashr_i32 s68, s4, 2
	s_mul_i32 s5, s68, s29
	s_sub_i32 s4, s4, s5
	s_add_i32 s69, s28, s4
